# MoBA unit prologue: Q row loads issued before the K/V LDS-DMAs and waited with vmcnt(7), so norm/gate/top-3 work overlaps the DMA latency
# baseline (speedup 1.0000x reference)
; template <int MODE> __device__ __forceinline__ void attn_unit(int b, int h, int qb, int t_lo, const bf16_t* Q, const bf16_t* __restrict__ K, const bf16_t* __restrict__ V, bf16_t* O, ATT_LAS unsigned char* lds, const int wid, const float kn2, const float bmax) {
;     ...
;     DMA_K(TILE(0), SLOT(0)); DMA_V(TILE(0), SLOT(0)); if (n > 1) { DMA_K(TILE(1), SLOT(1)); DMA_V(TILE(1), SLOT(1)); } if (n > 2) { DMA_K(TILE(2), SLOT(2)); DMA_V(TILE(2), SLOT(2)); } if (n > 3) DMA_K(TILE(3), SLOT(3));
;     bf16x8 qr[4];
; #pragma unroll
;     for (int d0 = 0; d0 < 4; ++d0) qr[d0] = *reinterpret_cast<const bf16x8*>(&Qw[(long)r32 * DM + d0 * 16 + hi * 8]);
;     asm volatile("" : "+v"(qr[0]), "+v"(qr[1]), "+v"(qr[2]), "+v"(qr[3]));
;     const int qrel = wid * QBLK + r32;
;     float ref;
;     { float qn2 = 0.f;
; #pragma unroll
;       for (int d0 = 0; d0 < 4; ++d0)
; #pragma unroll
;           for (int e = 0; e < 8; ++e) { const float v = __uint_as_float((unsigned)(unsigned short)qr[d0][e] << 16); qn2 += v * v; }
;       qn2 += pg8::xor_lane<32>(qn2);
;       ref = sqrtf(qn2 * kn2) * 1.02f - 64.f;
;       if (MODE == 0) ref -= ((const ATT_LAS float*)(lds + LDS_C))[q0 + qrel]; else ref += bmax; }
;     unsigned selm = 0u; float tb31 = 0.f;
;     if (MODE == 1) {
;         f32x16 g = {};
;         const lds_cptr kmp = (lds_cptr)lds + LDS_KM + (r32 & 15) * 128 + hi * 16;
; #pragma unroll
;         for (int d0 = 0; d0 < 4; ++d0) { const bf16x8 a = *(const ATT_LAS bf16x8*)(kmp + d0 * 32); g = ATT_MFMA(a, qr[d0], g); }
;         ATT_LAS float* gs = (ATT_LAS float*)(lds + LDS_OST + wid * 4096);
; #pragma unroll
;         for (int i = 0; i < 8; ++i) gs[r32 * 16 + crow(i, hi)] = g[i];
;         asm volatile("s_waitcnt lgkmcnt(0)" ::: "memory");
;         float gv[16];
; #pragma unroll
;         for (int i = 0; i < 4; ++i) { const f32x4 t4 = *(const ATT_LAS f32x4*)(gs + r32 * 16 + 4 * i); gv[4 * i] = t4[0]; gv[4 * i + 1] = t4[1]; gv[4 * i + 2] = t4[2]; gv[4 * i + 3] = t4[3]; }
; #pragma unroll
;         for (int k = 0; k < 3; ++k) { float best = -INFINITY; int bi = -1;
; #pragma unroll
;             for (int n = 0; n < 15; ++n) { const bool ok = (n < qb) && !((selm >> n) & 1u) && (gv[n] > best); best = ok ? gv[n] : best; bi = ok ? n : bi; }
;             if (bi >= 0) selm |= 1u << bi; }
;         tb31 = ((const ATT_LAS float*)(lds + LDS_TB))[256 + 127];
.LBB0_1052:
	s_mov_b32 s8, -1
	s_lshl_b32 s42, s91, 8
	v_mbcnt_lo_u32_b32 v0, s8, 0
	v_mbcnt_hi_u32_b32 v52, s8, v0
	s_add_u32 s8, s19, s42
	v_ashrrev_i32_e32 v53, 31, v52
	v_lshlrev_b64 v[0:1], 11, v[52:53]
	v_lshl_add_u64 v[48:49], s[10:11], 0, v[0:1]
	v_ashrrev_i32_e32 v0, 2, v52
	s_addc_u32 s9, s90, 0
	v_add_u32_e32 v0, s79, v0
	s_lshl_b64 s[8:9], s[8:9], 11
	v_ashrrev_i32_e32 v1, 31, v0
	v_lshlrev_b32_e32 v2, 3, v52
	s_add_u32 s28, s40, s8
	v_lshlrev_b64 v[0:1], 11, v[0:1]
	v_and_b32_e32 v53, 24, v2
	v_readfirstlane_b32 s8, v120
	s_addc_u32 s29, s41, s9
	v_ashrrev_i32_e32 v236, 5, v52
	v_lshlrev_b32_e32 v236, 3, v236
	v_ashrrev_i32_e32 v237, 31, v236
	v_lshl_add_u64 v[236:237], v[236:237], 1, s[28:29]
	v_and_b32_e32 v238, 31, v52
	v_lshlrev_b32_e32 v238, 11, v238
	v_mov_b32_e32 v239, 0
	v_lshl_add_u64 v[236:237], v[236:237], 0, v[238:239]
	global_load_dwordx4 v[80:83], v[236:237], off offset:96
	global_load_dwordx4 v[84:87], v[236:237], off offset:64
	global_load_dwordx4 v[88:91], v[236:237], off offset:32
	global_load_dwordx4 v[92:95], v[236:237], off
	v_lshl_add_u64 v[0:1], s[12:13], 0, v[0:1]
	v_lshlrev_b32_e32 v112, 1, v53
	s_mov_b32 s9, m0
	s_mov_b32 m0, s8
	s_nop 0
	global_load_lds_dwordx4 v[48:49], off
	s_mov_b32 m0, s9
	v_readfirstlane_b32 s8, v121
	v_lshl_add_u64 v[50:51], v[0:1], 0, v[112:113]
	s_mov_b32 s9, m0
	s_mov_b32 m0, s8
	s_nop 0
	global_load_lds_dwordx4 v[50:51], off
	s_mov_b32 m0, s9
	v_readfirstlane_b32 s8, v122
	v_lshl_add_u64 v[0:1], v[48:49], 0, s[22:23]
	s_add_i32 s8, s8, 0
	s_add_i32 s9, s8, 0x2000
	s_mov_b32 s30, m0
	s_mov_b32 m0, s9
	s_nop 0
	global_load_lds_dwordx4 v[0:1], off
	s_mov_b32 m0, s30
	v_lshl_add_u64 v[0:1], v[50:51], 0, s[22:23]
	s_add_i32 s9, s8, 0xa000
	s_mov_b32 s30, m0
	s_mov_b32 m0, s9
	s_nop 0
	global_load_lds_dwordx4 v[0:1], off
	s_mov_b32 m0, s30
	v_lshl_add_u64 v[0:1], v[48:49], 0, s[24:25]
	s_add_i32 s9, s8, 0x4000
	s_mov_b32 s30, m0
	s_mov_b32 m0, s9
	s_nop 0
	global_load_lds_dwordx4 v[0:1], off
	s_mov_b32 m0, s30
	v_lshl_add_u64 v[0:1], v[50:51], 0, s[24:25]
	v_ashrrev_i32_e32 v55, 5, v52
	s_add_i32 s9, s8, 0xc000
	s_mov_b32 s30, m0
	s_mov_b32 m0, s9
	s_nop 0
	global_load_lds_dwordx4 v[0:1], off
	s_mov_b32 m0, s30
	v_lshl_add_u64 v[0:1], v[48:49], 0, s[26:27]
	s_addk_i32 s8, 0x6000
	s_mov_b32 s9, m0
	s_mov_b32 m0, s8
	s_nop 0
	global_load_lds_dwordx4 v[0:1], off
	s_mov_b32 m0, s9
	v_lshlrev_b32_e32 v0, 3, v55
	v_and_b32_e32 v54, 31, v52
	v_ashrrev_i32_e32 v1, 31, v0
	v_lshl_add_u64 v[0:1], v[0:1], 1, s[28:29]
	v_lshlrev_b32_e32 v112, 11, v54
	v_lshl_add_u64 v[0:1], v[0:1], 0, v[112:113]
	v_lshlrev_b32_e32 v0, 7, v52
	v_and_b32_e32 v0, 0x780, v0
	v_lshlrev_b32_e32 v24, 4, v55
	v_add3_u32 v25, s87, v0, v24
	s_mov_b32 s8, 0xf800000
	s_waitcnt vmcnt(7)
	s_nop 0
	v_and_b32_e32 v9, 0xffff0000, v92
	v_lshlrev_b32_e32 v8, 16, v92
	v_mul_f32_e32 v46, v9, v9
	v_lshlrev_b32_e32 v10, 16, v93
	v_fmac_f32_e32 v46, v8, v8
	v_and_b32_e32 v11, 0xffff0000, v93
	v_fmac_f32_e32 v46, v10, v10
	v_lshlrev_b32_e32 v12, 16, v94
	v_fmac_f32_e32 v46, v11, v11
	v_and_b32_e32 v13, 0xffff0000, v94
	v_fmac_f32_e32 v46, v12, v12
	v_lshlrev_b32_e32 v14, 16, v95
	v_fmac_f32_e32 v46, v13, v13
	v_and_b32_e32 v15, 0xffff0000, v95
	v_fmac_f32_e32 v46, v14, v14
	v_lshlrev_b32_e32 v26, 16, v88
	v_fmac_f32_e32 v46, v15, v15
	v_and_b32_e32 v27, 0xffff0000, v88
	v_fmac_f32_e32 v46, v26, v26
	v_lshlrev_b32_e32 v28, 16, v89
	v_fmac_f32_e32 v46, v27, v27
	v_and_b32_e32 v29, 0xffff0000, v89
	v_fmac_f32_e32 v46, v28, v28
	v_lshlrev_b32_e32 v30, 16, v90
	v_fmac_f32_e32 v46, v29, v29
	v_and_b32_e32 v31, 0xffff0000, v90
	v_fmac_f32_e32 v46, v30, v30
	v_lshlrev_b32_e32 v32, 16, v91
	v_fmac_f32_e32 v46, v31, v31
	v_and_b32_e32 v33, 0xffff0000, v91
	v_fmac_f32_e32 v46, v32, v32
	v_lshlrev_b32_e32 v34, 16, v84
	v_fmac_f32_e32 v46, v33, v33
	v_and_b32_e32 v35, 0xffff0000, v84
	v_fmac_f32_e32 v46, v34, v34
	v_lshlrev_b32_e32 v36, 16, v85
	v_fmac_f32_e32 v46, v35, v35
	v_and_b32_e32 v37, 0xffff0000, v85
	v_fmac_f32_e32 v46, v36, v36
	v_lshlrev_b32_e32 v38, 16, v86
	v_fmac_f32_e32 v46, v37, v37
	v_and_b32_e32 v39, 0xffff0000, v86
	v_fmac_f32_e32 v46, v38, v38
	v_lshlrev_b32_e32 v40, 16, v87
	v_fmac_f32_e32 v46, v39, v39
	v_and_b32_e32 v41, 0xffff0000, v87
	v_fmac_f32_e32 v46, v40, v40
	v_lshlrev_b32_e32 v42, 16, v80
	v_fmac_f32_e32 v46, v41, v41
	v_and_b32_e32 v43, 0xffff0000, v80
	v_fmac_f32_e32 v46, v42, v42
	v_lshlrev_b32_e32 v44, 16, v81
	v_fmac_f32_e32 v46, v43, v43
	v_and_b32_e32 v45, 0xffff0000, v81
	v_and_b32_e32 v5, 0xffff0000, v82
	v_lshlrev_b32_e32 v4, 16, v82
	v_fmac_f32_e32 v46, v44, v44
	v_pk_mul_f32 v[20:21], v[4:5], v[4:5]
	v_fmac_f32_e32 v46, v45, v45
	ds_read_b128 v[0:3], v25
	ds_read_b128 v[16:19], v25 offset:32
	v_and_b32_e32 v7, 0xffff0000, v83
	v_lshlrev_b32_e32 v6, 16, v83
	v_add_f32_e32 v20, v20, v46
	v_pk_mul_f32 v[22:23], v[6:7], v[6:7]
	v_add_f32_e32 v20, v21, v20
	v_add_f32_e32 v20, v22, v20
	v_add_f32_e32 v20, v23, v20
	s_waitcnt lgkmcnt(1)
	v_mfma_f32_32x32x16_bf16 v[0:15], v[0:3], v[92:95], 0
	v_mov_b32_e32 v21, v20
	v_mov_b32_e32 v22, v20
	s_nop 1
	v_permlane32_swap_b32_e32 v21, v22
	v_xor_b32_e32 v21, v21, v22
	v_xor_b32_e32 v21, v21, v20
	v_add_f32_e32 v20, v20, v21
	v_mul_f32_e32 v20, v118, v20
	v_mul_f32_e32 v21, 0x4f800000, v20
	v_cmp_gt_f32_e32 vcc, s8, v20
	s_waitcnt lgkmcnt(0)
	v_mfma_f32_32x32x16_bf16 v[0:15], v[16:19], v[88:91], v[0:15]
	v_cndmask_b32_e32 v26, v20, v21, vcc
	ds_read_b128 v[20:23], v25 offset:64
	v_sqrt_f32_e32 v27, v26
	s_nop 0
	v_add_u32_e32 v16, -1, v27
	v_fma_f32 v17, -v16, v27, v26
	v_cmp_ge_f32_e64 s[8:9], 0, v17
	v_add_u32_e32 v29, 1, v27
	s_nop 0
	v_cndmask_b32_e64 v28, v27, v16, s[8:9]
	ds_read_b128 v[16:19], v25 offset:96
	s_waitcnt lgkmcnt(1)
	v_mfma_f32_32x32x16_bf16 v[0:15], v[20:23], v[84:87], v[0:15]
	v_fma_f32 v27, -v29, v27, v26
	v_cmp_lt_f32_e64 s[8:9], 0, v27
	s_nop 1
	v_cndmask_b32_e64 v20, v28, v29, s[8:9]
	v_mul_f32_e32 v21, 0x37800000, v20
	v_cndmask_b32_e32 v20, v20, v21, vcc
	s_waitcnt lgkmcnt(0)
	v_mfma_f32_32x32x16_bf16 v[0:15], v[16:19], v[80:83], v[0:15]
	v_cmp_class_f32_e32 vcc, v26, v123
	s_nop 1
	v_cndmask_b32_e32 v20, v20, v26, vcc
	v_fmamk_f32 v32, v20, 0x3f828f5c, v124
	s_nop 6
	v_lshl_add_u32 v8, v54, 6, s81
	v_add_u32_e32 v9, v8, v24
	ds_write_b128 v9, v[0:3]
	ds_write_b128 v9, v[4:7] offset:32
	s_waitcnt lgkmcnt(0)
	ds_read_b128 v[28:31], v8
	ds_read_b128 v[24:27], v8 offset:16
	ds_read_b128 v[20:23], v8 offset:32
	ds_read_b128 v[16:19], v8 offset:48
	v_add_f32_e32 v0, v119, v32
	ds_read_b32 v128, v125
	v_xor_b32_e32 v0, 0x80000000, v0
	v_mov_b32_e32 v1, v0
	v_mov_b32_e32 v2, v0
	v_mov_b32_e32 v3, v0
	v_mov_b32_e32 v4, v0
	v_mov_b32_e32 v5, v0
	v_mov_b32_e32 v6, v0
	v_mov_b32_e32 v7, v0
	v_mov_b32_e32 v8, v0
	v_mov_b32_e32 v9, v0
	v_mov_b32_e32 v10, v0
	v_mov_b32_e32 v11, v0
	v_mov_b32_e32 v12, v0
	v_mov_b32_e32 v13, v0
	v_mov_b32_e32 v14, v0
	v_mov_b32_e32 v15, v0
	s_waitcnt lgkmcnt(0)
	s_waitcnt vmcnt(0) lgkmcnt(0)
	s_barrier
	s_and_b64 vcc, exec, s[6:7]
	s_cbranch_vccnz .LBB0_1054
	s_barrier

; template <int MODE> __device__ __forceinline__ void attn_unit(int b, int h, int qb, int t_lo, const bf16_t* Q, const bf16_t* __restrict__ K, const bf16_t* __restrict__ V, bf16_t* O, ATT_LAS unsigned char* lds, const int wid, const float kn2, const float bmax) {
;     ...
;     DMA_K(TILE(0), SLOT(0)); DMA_V(TILE(0), SLOT(0)); if (n > 1) { DMA_K(TILE(1), SLOT(1)); DMA_V(TILE(1), SLOT(1)); } if (n > 2) { DMA_K(TILE(2), SLOT(2)); DMA_V(TILE(2), SLOT(2)); } if (n > 3) DMA_K(TILE(3), SLOT(3));
;     bf16x8 qr[4];
; #pragma unroll
;     for (int d0 = 0; d0 < 4; ++d0) qr[d0] = *reinterpret_cast<const bf16x8*>(&Qw[(long)r32 * DM + d0 * 16 + hi * 8]);
;     asm volatile("" : "+v"(qr[0]), "+v"(qr[1]), "+v"(qr[2]), "+v"(qr[3]));
;     const int qrel = wid * QBLK + r32;
;     float ref;
;     { float qn2 = 0.f;
; #pragma unroll
;       for (int d0 = 0; d0 < 4; ++d0)
; #pragma unroll
;           for (int e = 0; e < 8; ++e) { const float v = __uint_as_float((unsigned)(unsigned short)qr[d0][e] << 16); qn2 += v * v; }
;       qn2 += pg8::xor_lane<32>(qn2);
;       ref = sqrtf(qn2 * kn2) * 1.02f - 64.f;
;       if (MODE == 0) ref -= ((const ATT_LAS float*)(lds + LDS_C))[q0 + qrel]; else ref += bmax; }
;     unsigned selm = 0u; float tb31 = 0.f;
;     if (MODE == 1) {
;         f32x16 g = {};
;         const lds_cptr kmp = (lds_cptr)lds + LDS_KM + (r32 & 15) * 128 + hi * 16;
; #pragma unroll
;         for (int d0 = 0; d0 < 4; ++d0) { const bf16x8 a = *(const ATT_LAS bf16x8*)(kmp + d0 * 32); g = ATT_MFMA(a, qr[d0], g); }
;         ATT_LAS float* gs = (ATT_LAS float*)(lds + LDS_OST + wid * 4096);
; #pragma unroll
;         for (int i = 0; i < 8; ++i) gs[r32 * 16 + crow(i, hi)] = g[i];
;         asm volatile("s_waitcnt lgkmcnt(0)" ::: "memory");
;         float gv[16];
; #pragma unroll
;         for (int i = 0; i < 4; ++i) { const f32x4 t4 = *(const ATT_LAS f32x4*)(gs + r32 * 16 + 4 * i); gv[4 * i] = t4[0]; gv[4 * i + 1] = t4[1]; gv[4 * i + 2] = t4[2]; gv[4 * i + 3] = t4[3]; }
; #pragma unroll
;         for (int k = 0; k < 3; ++k) { float best = -INFINITY; int bi = -1;
; #pragma unroll
;             for (int n = 0; n < 15; ++n) { const bool ok = (n < qb) && !((selm >> n) & 1u) && (gv[n] > best); best = ok ? gv[n] : best; bi = ok ? n : bi; }
;             if (bi >= 0) selm |= 1u << bi; }
;         tb31 = ((const ATT_LAS float*)(lds + LDS_TB))[256 + 127];
.LBB0_2376:
	s_mov_b32 s10, -1
	s_lshl_b32 s42, s93, 8
	v_mbcnt_lo_u32_b32 v0, s10, 0
	v_mbcnt_hi_u32_b32 v52, s10, v0
	s_add_u32 s10, s85, s42
	v_ashrrev_i32_e32 v53, 31, v52
	v_lshlrev_b64 v[0:1], 11, v[52:53]
	v_lshl_add_u64 v[48:49], s[12:13], 0, v[0:1]
	v_ashrrev_i32_e32 v0, 2, v52
	s_addc_u32 s11, s92, 0
	v_add_u32_e32 v0, s79, v0
	s_lshl_b64 s[10:11], s[10:11], 11
	v_ashrrev_i32_e32 v1, 31, v0
	v_lshlrev_b32_e32 v2, 3, v52
	s_add_u32 s26, s41, s10
	v_lshlrev_b64 v[0:1], 11, v[0:1]
	v_and_b32_e32 v53, 24, v2
	v_readfirstlane_b32 s10, v120
	s_addc_u32 s27, s76, s11
	v_ashrrev_i32_e32 v236, 5, v52
	v_lshlrev_b32_e32 v236, 3, v236
	v_ashrrev_i32_e32 v237, 31, v236
	v_lshl_add_u64 v[236:237], v[236:237], 1, s[26:27]
	v_and_b32_e32 v238, 31, v52
	v_lshlrev_b32_e32 v238, 11, v238
	v_mov_b32_e32 v239, 0
	v_lshl_add_u64 v[236:237], v[236:237], 0, v[238:239]
	global_load_dwordx4 v[80:83], v[236:237], off offset:96
	global_load_dwordx4 v[84:87], v[236:237], off offset:64
	global_load_dwordx4 v[88:91], v[236:237], off offset:32
	global_load_dwordx4 v[92:95], v[236:237], off
	v_lshl_add_u64 v[0:1], s[18:19], 0, v[0:1]
	v_lshlrev_b32_e32 v112, 1, v53
	s_mov_b32 s11, m0
	s_mov_b32 m0, s10
	s_nop 0
	global_load_lds_dwordx4 v[48:49], off
	s_mov_b32 m0, s11
	v_readfirstlane_b32 s10, v121
	v_lshl_add_u64 v[50:51], v[0:1], 0, v[112:113]
	s_mov_b32 s11, m0
	s_mov_b32 m0, s10
	s_nop 0
	global_load_lds_dwordx4 v[50:51], off
	s_mov_b32 m0, s11
	v_readfirstlane_b32 s10, v122
	v_lshl_add_u64 v[0:1], v[48:49], 0, s[20:21]
	s_add_i32 s10, s10, 0
	s_add_i32 s11, s10, 0x2000
	s_mov_b32 s28, m0
	s_mov_b32 m0, s11
	s_nop 0
	global_load_lds_dwordx4 v[0:1], off
	s_mov_b32 m0, s28
	v_lshl_add_u64 v[0:1], v[50:51], 0, s[20:21]
	s_add_i32 s11, s10, 0xa000
	s_mov_b32 s28, m0
	s_mov_b32 m0, s11
	s_nop 0
	global_load_lds_dwordx4 v[0:1], off
	s_mov_b32 m0, s28
	v_lshl_add_u64 v[0:1], v[48:49], 0, s[22:23]
	s_add_i32 s11, s10, 0x4000
	s_mov_b32 s28, m0
	s_mov_b32 m0, s11
	s_nop 0
	global_load_lds_dwordx4 v[0:1], off
	s_mov_b32 m0, s28
	v_lshl_add_u64 v[0:1], v[50:51], 0, s[22:23]
	v_ashrrev_i32_e32 v55, 5, v52
	s_add_i32 s11, s10, 0xc000
	s_mov_b32 s28, m0
	s_mov_b32 m0, s11
	s_nop 0
	global_load_lds_dwordx4 v[0:1], off
	s_mov_b32 m0, s28
	v_lshl_add_u64 v[0:1], v[48:49], 0, s[24:25]
	s_addk_i32 s10, 0x6000
	s_mov_b32 s11, m0
	s_mov_b32 m0, s10
	s_nop 0
	global_load_lds_dwordx4 v[0:1], off
	s_mov_b32 m0, s11
	v_lshlrev_b32_e32 v0, 3, v55
	v_and_b32_e32 v54, 31, v52
	v_ashrrev_i32_e32 v1, 31, v0
	v_lshl_add_u64 v[0:1], v[0:1], 1, s[26:27]
	v_lshlrev_b32_e32 v112, 11, v54
	v_lshl_add_u64 v[0:1], v[0:1], 0, v[112:113]
	v_lshlrev_b32_e32 v0, 7, v52
	v_and_b32_e32 v0, 0x780, v0
	v_lshlrev_b32_e32 v24, 4, v55
	v_add3_u32 v25, s87, v0, v24
	s_mov_b32 s10, 0xf800000
	s_waitcnt vmcnt(7)
	s_nop 0
	v_and_b32_e32 v9, 0xffff0000, v92
	v_lshlrev_b32_e32 v8, 16, v92
	v_mul_f32_e32 v46, v9, v9
	v_lshlrev_b32_e32 v10, 16, v93
	v_fmac_f32_e32 v46, v8, v8
	v_and_b32_e32 v11, 0xffff0000, v93
	v_fmac_f32_e32 v46, v10, v10
	v_lshlrev_b32_e32 v12, 16, v94
	v_fmac_f32_e32 v46, v11, v11
	v_and_b32_e32 v13, 0xffff0000, v94
	v_fmac_f32_e32 v46, v12, v12
	v_lshlrev_b32_e32 v14, 16, v95
	v_fmac_f32_e32 v46, v13, v13
	v_and_b32_e32 v15, 0xffff0000, v95
	v_fmac_f32_e32 v46, v14, v14
	v_lshlrev_b32_e32 v26, 16, v88
	v_fmac_f32_e32 v46, v15, v15
	v_and_b32_e32 v27, 0xffff0000, v88
	v_fmac_f32_e32 v46, v26, v26
	v_lshlrev_b32_e32 v28, 16, v89
	v_fmac_f32_e32 v46, v27, v27
	v_and_b32_e32 v29, 0xffff0000, v89
	v_fmac_f32_e32 v46, v28, v28
	v_lshlrev_b32_e32 v30, 16, v90
	v_fmac_f32_e32 v46, v29, v29
	v_and_b32_e32 v31, 0xffff0000, v90
	v_fmac_f32_e32 v46, v30, v30
	v_lshlrev_b32_e32 v32, 16, v91
	v_fmac_f32_e32 v46, v31, v31
	v_and_b32_e32 v33, 0xffff0000, v91
	v_fmac_f32_e32 v46, v32, v32
	v_lshlrev_b32_e32 v34, 16, v84
	v_fmac_f32_e32 v46, v33, v33
	v_and_b32_e32 v35, 0xffff0000, v84
	v_fmac_f32_e32 v46, v34, v34
	v_lshlrev_b32_e32 v36, 16, v85
	v_fmac_f32_e32 v46, v35, v35
	v_and_b32_e32 v37, 0xffff0000, v85
	v_fmac_f32_e32 v46, v36, v36
	v_lshlrev_b32_e32 v38, 16, v86
	v_fmac_f32_e32 v46, v37, v37
	v_and_b32_e32 v39, 0xffff0000, v86
	v_fmac_f32_e32 v46, v38, v38
	v_lshlrev_b32_e32 v40, 16, v87
	v_fmac_f32_e32 v46, v39, v39
	v_and_b32_e32 v41, 0xffff0000, v87
	v_fmac_f32_e32 v46, v40, v40
	v_lshlrev_b32_e32 v42, 16, v80
	v_fmac_f32_e32 v46, v41, v41
	v_and_b32_e32 v43, 0xffff0000, v80
	v_fmac_f32_e32 v46, v42, v42
	v_lshlrev_b32_e32 v44, 16, v81
	v_fmac_f32_e32 v46, v43, v43
	v_and_b32_e32 v45, 0xffff0000, v81
	v_and_b32_e32 v5, 0xffff0000, v82
	v_lshlrev_b32_e32 v4, 16, v82
	v_fmac_f32_e32 v46, v44, v44
	v_pk_mul_f32 v[20:21], v[4:5], v[4:5]
	v_fmac_f32_e32 v46, v45, v45
	ds_read_b128 v[0:3], v25
	ds_read_b128 v[16:19], v25 offset:32
	v_and_b32_e32 v7, 0xffff0000, v83
	v_lshlrev_b32_e32 v6, 16, v83
	v_add_f32_e32 v20, v20, v46
	v_pk_mul_f32 v[22:23], v[6:7], v[6:7]
	v_add_f32_e32 v20, v21, v20
	v_add_f32_e32 v20, v22, v20
	v_add_f32_e32 v20, v23, v20
	s_waitcnt lgkmcnt(1)
	v_mfma_f32_32x32x16_bf16 v[0:15], v[0:3], v[92:95], 0
	v_mov_b32_e32 v21, v20
	v_mov_b32_e32 v22, v20
	s_nop 1
	v_permlane32_swap_b32_e32 v21, v22
	v_xor_b32_e32 v21, v21, v22
	v_xor_b32_e32 v21, v21, v20
	v_add_f32_e32 v20, v20, v21
	v_mul_f32_e32 v20, v118, v20
	v_mul_f32_e32 v21, 0x4f800000, v20
	v_cmp_gt_f32_e32 vcc, s10, v20
	s_waitcnt lgkmcnt(0)
	v_mfma_f32_32x32x16_bf16 v[0:15], v[16:19], v[88:91], v[0:15]
	v_cndmask_b32_e32 v26, v20, v21, vcc
	ds_read_b128 v[20:23], v25 offset:64
	v_sqrt_f32_e32 v27, v26
	s_nop 0
	v_add_u32_e32 v16, -1, v27
	v_fma_f32 v17, -v16, v27, v26
	v_cmp_ge_f32_e64 s[10:11], 0, v17
	v_add_u32_e32 v29, 1, v27
	s_nop 0
	v_cndmask_b32_e64 v28, v27, v16, s[10:11]
	ds_read_b128 v[16:19], v25 offset:96
	s_waitcnt lgkmcnt(1)
	v_mfma_f32_32x32x16_bf16 v[0:15], v[20:23], v[84:87], v[0:15]
	v_fma_f32 v27, -v29, v27, v26
	v_cmp_lt_f32_e64 s[10:11], 0, v27
	s_nop 1
	v_cndmask_b32_e64 v20, v28, v29, s[10:11]
	v_mul_f32_e32 v21, 0x37800000, v20
	v_cndmask_b32_e32 v20, v20, v21, vcc
	s_waitcnt lgkmcnt(0)
	v_mfma_f32_32x32x16_bf16 v[0:15], v[16:19], v[80:83], v[0:15]
	v_cmp_class_f32_e32 vcc, v26, v123
	s_nop 1
	v_cndmask_b32_e32 v20, v20, v26, vcc
	v_fmamk_f32 v32, v20, 0x3f828f5c, v124
	s_nop 6
	v_lshl_add_u32 v8, v54, 6, s81
	v_add_u32_e32 v9, v8, v24
	ds_write_b128 v9, v[0:3]
	ds_write_b128 v9, v[4:7] offset:32
	s_waitcnt lgkmcnt(0)
	ds_read_b128 v[28:31], v8
	ds_read_b128 v[24:27], v8 offset:16
	ds_read_b128 v[20:23], v8 offset:32
	ds_read_b128 v[16:19], v8 offset:48
	v_add_f32_e32 v0, v119, v32
	ds_read_b32 v128, v125
	v_xor_b32_e32 v0, 0x80000000, v0
	v_mov_b32_e32 v1, v0
	v_mov_b32_e32 v2, v0
	v_mov_b32_e32 v3, v0
	v_mov_b32_e32 v4, v0
	v_mov_b32_e32 v5, v0
	v_mov_b32_e32 v6, v0
	v_mov_b32_e32 v7, v0
	v_mov_b32_e32 v8, v0
	v_mov_b32_e32 v9, v0
	v_mov_b32_e32 v10, v0
	v_mov_b32_e32 v11, v0
	v_mov_b32_e32 v12, v0
	v_mov_b32_e32 v13, v0
	v_mov_b32_e32 v14, v0
	v_mov_b32_e32 v15, v0
	s_waitcnt lgkmcnt(0)
	s_waitcnt vmcnt(0) lgkmcnt(0)
	s_barrier
; template <int MODE> __device__ __forceinline__ void attn_unit(int b, int h, int qb, int t_lo, const bf16_t* Q, const bf16_t* __restrict__ K, const bf16_t* __restrict__ V, bf16_t* O, ATT_LAS unsigned char* lds, const int wid, const float kn2, const float bmax) {
;     ...
;     asm volatile("s_waitcnt vmcnt(0) lgkmcnt(0)\n\ts_barrier" ::: "memory");
;     if (grp == 1) asm volatile("s_barrier" ::: "memory");
	s_and_b64 vcc, exec, s[6:7]
	s_cbranch_vccnz .LBB0_2378
	s_barrier
